# scanner: tight dependent packed ops with the LDS group mid-chain (24.2 instr per step)
# speedup vs baseline: 1.0122x; 1.0122x over previous
.LBB0_787:
	s_and_saveexec_b64 s[0:1], s[8:9]
	s_xor_b64 s[36:37], exec, s[0:1]
	s_cbranch_execz .LBB0_791
	s_and_saveexec_b64 s[44:45], s[26:27]
	s_cbranch_execz .LBB0_790
	s_and_b32 s0, s54, 1
	s_mul_i32 s1, s0, 0xc000
	s_lshl_b32 s4, s30, 2
	v_add_u32_e32 v10, s1, v97
	s_add_i32 s1, s1, s4
	v_lshl_add_u32 v11, v95, 2, s1
	v_lshl_add_u32 v12, s0, 14, v102
	v_pk_fma_f32 v[4:5], v[60:61], v[64:65], v[56:57] op_sel_hi:[0,1,1]
	v_pk_fma_f32 v[6:7], v[60:61], v[66:67], v[58:59] op_sel_hi:[0,1,1]
	v_pk_mul_f32 v[80:81], v[4:5], v[80:81]
	v_pk_fma_f32 v[80:81], v[6:7], v[82:83], v[80:81]
	v_add_f32_e32 v80, v80, v81
	v_pk_mul_f32 v[76:77], v[76:77], v[2:3] op_sel_hi:[1,0]
	v_pk_mul_f32 v[78:79], v[78:79], v[2:3] op_sel_hi:[1,0]
	v_add_f32_dpp v80, v80, v80 quad_perm:[1,0,3,2] row_mask:0xf bank_mask:0xf bound_ctrl:1
	v_pk_fma_f32 v[76:77], v[4:5], v[68:69], v[76:77]
	v_pk_fma_f32 v[78:79], v[6:7], v[70:71], v[78:79]
	v_add_f32_dpp v80, v80, v80 quad_perm:[2,3,0,1] row_mask:0xf bank_mask:0xf bound_ctrl:1
	v_pk_mul_f32 v[52:53], v[52:53], v[4:5]
	v_pk_fma_f32 v[52:53], v[6:7], v[54:55], v[52:53]
	ds_read_b128 v[36:39], v10 offset:512
	ds_read2st64_b32 v[0:1], v11 offset0:5 offset1:11
	ds_read_b128 v[40:43], v10 offset:768
	ds_read_b128 v[28:31], v10 offset:0
	ds_read_b128 v[44:47], v10 offset:1024
	ds_read_b128 v[32:35], v10 offset:256
	v_add_f32_dpp v80, v80, v80 row_half_mirror row_mask:0xf bank_mask:0xf bound_ctrl:1
	v_add_f32_e32 v9, v52, v53
	s_nop 0
	v_add_f32_dpp v80, v80, v80 row_mirror row_mask:0xf bank_mask:0xf bound_ctrl:1
	v_pk_fma_f32 v[4:5], v[80:81], v[84:85], v[76:77] op_sel_hi:[0,1,1]
	v_pk_fma_f32 v[6:7], v[80:81], v[86:87], v[78:79] op_sel_hi:[0,1,1]
	v_pk_mul_f32 v[116:117], v[4:5], v[116:117]
	v_pk_fma_f32 v[116:117], v[6:7], v[118:119], v[116:117]
	v_add_f32_e32 v116, v116, v117
	v_pk_mul_f32 v[112:113], v[112:113], v[2:3] op_sel:[0,1] op_sel_hi:[1,1]
	v_pk_mul_f32 v[114:115], v[114:115], v[2:3] op_sel:[0,1] op_sel_hi:[1,1]
	v_add_f32_dpp v116, v116, v116 quad_perm:[1,0,3,2] row_mask:0xf bank_mask:0xf bound_ctrl:1
	v_pk_fma_f32 v[112:113], v[4:5], v[104:105], v[112:113]
	v_pk_fma_f32 v[114:115], v[6:7], v[106:107], v[114:115]
	v_add_f32_dpp v116, v116, v116 quad_perm:[2,3,0,1] row_mask:0xf bank_mask:0xf bound_ctrl:1
	v_pk_mul_f32 v[72:73], v[72:73], v[4:5]
	v_pk_fma_f32 v[72:73], v[6:7], v[74:75], v[72:73]
	ds_read_b128 v[56:59], v10 offset:2048
	ds_read_b128 v[60:63], v10 offset:2304
	ds_read_b128 v[48:51], v10 offset:1536
	ds_read_b128 v[64:67], v10 offset:2560
	ds_read_b128 v[52:55], v10 offset:1792
	ds_write2st64_b32 v12, v8, v9 offset0:0 offset1:2
	v_add_f32_dpp v116, v116, v116 row_half_mirror row_mask:0xf bank_mask:0xf bound_ctrl:1
	v_add_f32_e32 v8, v72, v73
	s_nop 0
	v_add_f32_dpp v116, v116, v116 row_mirror row_mask:0xf bank_mask:0xf bound_ctrl:1
	v_pk_fma_f32 v[4:5], v[116:117], v[120:121], v[112:113] op_sel_hi:[0,1,1]
	v_pk_fma_f32 v[6:7], v[116:117], v[122:123], v[114:115] op_sel_hi:[0,1,1]
	s_waitcnt lgkmcnt(6)
	v_pk_mul_f32 v[40:41], v[4:5], v[40:41]
	v_pk_fma_f32 v[40:41], v[6:7], v[42:43], v[40:41]
	v_add_f32_e32 v40, v40, v41
	v_pk_mul_f32 v[36:37], v[36:37], v[0:1] op_sel_hi:[1,0]
	v_pk_mul_f32 v[38:39], v[38:39], v[0:1] op_sel_hi:[1,0]
	v_add_f32_dpp v40, v40, v40 quad_perm:[1,0,3,2] row_mask:0xf bank_mask:0xf bound_ctrl:1
	v_pk_fma_f32 v[36:37], v[4:5], v[28:29], v[36:37]
	v_pk_fma_f32 v[38:39], v[6:7], v[30:31], v[38:39]
	v_add_f32_dpp v40, v40, v40 quad_perm:[2,3,0,1] row_mask:0xf bank_mask:0xf bound_ctrl:1
	v_pk_mul_f32 v[108:109], v[108:109], v[4:5]
	v_pk_fma_f32 v[108:109], v[6:7], v[110:111], v[108:109]
	ds_read_b128 v[76:79], v10 offset:3584
	ds_read2st64_b32 v[2:3], v11 offset0:17 offset1:23
	ds_read_b128 v[80:83], v10 offset:3840
	ds_read_b128 v[68:71], v10 offset:3072
	ds_read_b128 v[84:87], v10 offset:4096
	ds_read_b128 v[72:75], v10 offset:3328
	v_add_f32_dpp v40, v40, v40 row_half_mirror row_mask:0xf bank_mask:0xf bound_ctrl:1
	v_add_f32_e32 v9, v108, v109
	s_nop 0
	v_add_f32_dpp v40, v40, v40 row_mirror row_mask:0xf bank_mask:0xf bound_ctrl:1
	v_pk_fma_f32 v[4:5], v[40:41], v[44:45], v[36:37] op_sel_hi:[0,1,1]
	v_pk_fma_f32 v[6:7], v[40:41], v[46:47], v[38:39] op_sel_hi:[0,1,1]
	s_waitcnt lgkmcnt(7)
	v_pk_mul_f32 v[60:61], v[4:5], v[60:61]
	v_pk_fma_f32 v[60:61], v[6:7], v[62:63], v[60:61]
	v_add_f32_e32 v60, v60, v61
	v_pk_mul_f32 v[56:57], v[56:57], v[0:1] op_sel:[0,1] op_sel_hi:[1,1]
	v_pk_mul_f32 v[58:59], v[58:59], v[0:1] op_sel:[0,1] op_sel_hi:[1,1]
	v_add_f32_dpp v60, v60, v60 quad_perm:[1,0,3,2] row_mask:0xf bank_mask:0xf bound_ctrl:1
	v_pk_fma_f32 v[56:57], v[4:5], v[48:49], v[56:57]
	v_pk_fma_f32 v[58:59], v[6:7], v[50:51], v[58:59]
	v_add_f32_dpp v60, v60, v60 quad_perm:[2,3,0,1] row_mask:0xf bank_mask:0xf bound_ctrl:1
	v_pk_mul_f32 v[32:33], v[32:33], v[4:5]
	v_pk_fma_f32 v[32:33], v[6:7], v[34:35], v[32:33]
	ds_read_b128 v[112:115], v10 offset:5120
	ds_read_b128 v[116:119], v10 offset:5376
	ds_read_b128 v[104:107], v10 offset:4608
	ds_read_b128 v[120:123], v10 offset:5632
	ds_read_b128 v[108:111], v10 offset:4864
	ds_write2st64_b32 v12, v8, v9 offset0:4 offset1:6
	v_add_f32_dpp v60, v60, v60 row_half_mirror row_mask:0xf bank_mask:0xf bound_ctrl:1
	v_add_f32_e32 v8, v32, v33
	s_nop 0
	v_add_f32_dpp v60, v60, v60 row_mirror row_mask:0xf bank_mask:0xf bound_ctrl:1
	v_pk_fma_f32 v[4:5], v[60:61], v[64:65], v[56:57] op_sel_hi:[0,1,1]
	v_pk_fma_f32 v[6:7], v[60:61], v[66:67], v[58:59] op_sel_hi:[0,1,1]
	s_waitcnt lgkmcnt(6)
	v_pk_mul_f32 v[80:81], v[4:5], v[80:81]
	v_pk_fma_f32 v[80:81], v[6:7], v[82:83], v[80:81]
	v_add_f32_e32 v80, v80, v81
	v_pk_mul_f32 v[76:77], v[76:77], v[2:3] op_sel_hi:[1,0]
	v_pk_mul_f32 v[78:79], v[78:79], v[2:3] op_sel_hi:[1,0]
	v_add_f32_dpp v80, v80, v80 quad_perm:[1,0,3,2] row_mask:0xf bank_mask:0xf bound_ctrl:1
	v_pk_fma_f32 v[76:77], v[4:5], v[68:69], v[76:77]
	v_pk_fma_f32 v[78:79], v[6:7], v[70:71], v[78:79]
	v_add_f32_dpp v80, v80, v80 quad_perm:[2,3,0,1] row_mask:0xf bank_mask:0xf bound_ctrl:1
	v_pk_mul_f32 v[52:53], v[52:53], v[4:5]
	v_pk_fma_f32 v[52:53], v[6:7], v[54:55], v[52:53]
	ds_read_b128 v[36:39], v10 offset:6656
	ds_read2st64_b32 v[0:1], v11 offset0:29 offset1:35
	ds_read_b128 v[40:43], v10 offset:6912
	ds_read_b128 v[28:31], v10 offset:6144
	ds_read_b128 v[44:47], v10 offset:7168
	ds_read_b128 v[32:35], v10 offset:6400
	v_add_f32_dpp v80, v80, v80 row_half_mirror row_mask:0xf bank_mask:0xf bound_ctrl:1
	v_add_f32_e32 v9, v52, v53
	s_nop 0
	v_add_f32_dpp v80, v80, v80 row_mirror row_mask:0xf bank_mask:0xf bound_ctrl:1
	v_pk_fma_f32 v[4:5], v[80:81], v[84:85], v[76:77] op_sel_hi:[0,1,1]
	v_pk_fma_f32 v[6:7], v[80:81], v[86:87], v[78:79] op_sel_hi:[0,1,1]
	s_waitcnt lgkmcnt(7)
	v_pk_mul_f32 v[116:117], v[4:5], v[116:117]
	v_pk_fma_f32 v[116:117], v[6:7], v[118:119], v[116:117]
	v_add_f32_e32 v116, v116, v117
	v_pk_mul_f32 v[112:113], v[112:113], v[2:3] op_sel:[0,1] op_sel_hi:[1,1]
	v_pk_mul_f32 v[114:115], v[114:115], v[2:3] op_sel:[0,1] op_sel_hi:[1,1]
	v_add_f32_dpp v116, v116, v116 quad_perm:[1,0,3,2] row_mask:0xf bank_mask:0xf bound_ctrl:1
	v_pk_fma_f32 v[112:113], v[4:5], v[104:105], v[112:113]
	v_pk_fma_f32 v[114:115], v[6:7], v[106:107], v[114:115]
	v_add_f32_dpp v116, v116, v116 quad_perm:[2,3,0,1] row_mask:0xf bank_mask:0xf bound_ctrl:1
	v_pk_mul_f32 v[72:73], v[72:73], v[4:5]
	v_pk_fma_f32 v[72:73], v[6:7], v[74:75], v[72:73]
	ds_read_b128 v[56:59], v10 offset:8192
	ds_read_b128 v[60:63], v10 offset:8448
	ds_read_b128 v[48:51], v10 offset:7680
	ds_read_b128 v[64:67], v10 offset:8704
	ds_read_b128 v[52:55], v10 offset:7936
	ds_write2st64_b32 v12, v8, v9 offset0:8 offset1:10
	v_add_f32_dpp v116, v116, v116 row_half_mirror row_mask:0xf bank_mask:0xf bound_ctrl:1
	v_add_f32_e32 v8, v72, v73
	s_nop 0
	v_add_f32_dpp v116, v116, v116 row_mirror row_mask:0xf bank_mask:0xf bound_ctrl:1
	v_pk_fma_f32 v[4:5], v[116:117], v[120:121], v[112:113] op_sel_hi:[0,1,1]
	v_pk_fma_f32 v[6:7], v[116:117], v[122:123], v[114:115] op_sel_hi:[0,1,1]
	s_waitcnt lgkmcnt(6)
	v_pk_mul_f32 v[40:41], v[4:5], v[40:41]
	v_pk_fma_f32 v[40:41], v[6:7], v[42:43], v[40:41]
	v_add_f32_e32 v40, v40, v41
	v_pk_mul_f32 v[36:37], v[36:37], v[0:1] op_sel_hi:[1,0]
	v_pk_mul_f32 v[38:39], v[38:39], v[0:1] op_sel_hi:[1,0]
	v_add_f32_dpp v40, v40, v40 quad_perm:[1,0,3,2] row_mask:0xf bank_mask:0xf bound_ctrl:1
	v_pk_fma_f32 v[36:37], v[4:5], v[28:29], v[36:37]
	v_pk_fma_f32 v[38:39], v[6:7], v[30:31], v[38:39]
	v_add_f32_dpp v40, v40, v40 quad_perm:[2,3,0,1] row_mask:0xf bank_mask:0xf bound_ctrl:1
	v_pk_mul_f32 v[108:109], v[108:109], v[4:5]
	v_pk_fma_f32 v[108:109], v[6:7], v[110:111], v[108:109]
	ds_read_b128 v[76:79], v10 offset:9728
	ds_read2st64_b32 v[2:3], v11 offset0:41 offset1:47
	ds_read_b128 v[80:83], v10 offset:9984
	ds_read_b128 v[68:71], v10 offset:9216
	ds_read_b128 v[84:87], v10 offset:10240
	ds_read_b128 v[72:75], v10 offset:9472
	v_add_f32_dpp v40, v40, v40 row_half_mirror row_mask:0xf bank_mask:0xf bound_ctrl:1
	v_add_f32_e32 v9, v108, v109
	s_nop 0
	v_add_f32_dpp v40, v40, v40 row_mirror row_mask:0xf bank_mask:0xf bound_ctrl:1
	v_pk_fma_f32 v[4:5], v[40:41], v[44:45], v[36:37] op_sel_hi:[0,1,1]
	v_pk_fma_f32 v[6:7], v[40:41], v[46:47], v[38:39] op_sel_hi:[0,1,1]
	s_waitcnt lgkmcnt(7)
	v_pk_mul_f32 v[60:61], v[4:5], v[60:61]
	v_pk_fma_f32 v[60:61], v[6:7], v[62:63], v[60:61]
	v_add_f32_e32 v60, v60, v61
	v_pk_mul_f32 v[56:57], v[56:57], v[0:1] op_sel:[0,1] op_sel_hi:[1,1]
	v_pk_mul_f32 v[58:59], v[58:59], v[0:1] op_sel:[0,1] op_sel_hi:[1,1]
	v_add_f32_dpp v60, v60, v60 quad_perm:[1,0,3,2] row_mask:0xf bank_mask:0xf bound_ctrl:1
	v_pk_fma_f32 v[56:57], v[4:5], v[48:49], v[56:57]
	v_pk_fma_f32 v[58:59], v[6:7], v[50:51], v[58:59]
	v_add_f32_dpp v60, v60, v60 quad_perm:[2,3,0,1] row_mask:0xf bank_mask:0xf bound_ctrl:1
	v_pk_mul_f32 v[32:33], v[32:33], v[4:5]
	v_pk_fma_f32 v[32:33], v[6:7], v[34:35], v[32:33]
	ds_read_b128 v[112:115], v10 offset:11264
	ds_read_b128 v[116:119], v10 offset:11520
	ds_read_b128 v[104:107], v10 offset:10752
	ds_read_b128 v[120:123], v10 offset:11776
	ds_read_b128 v[108:111], v10 offset:11008
	ds_write2st64_b32 v12, v8, v9 offset0:12 offset1:14
	v_add_f32_dpp v60, v60, v60 row_half_mirror row_mask:0xf bank_mask:0xf bound_ctrl:1
	v_add_f32_e32 v8, v32, v33
	s_nop 0
	v_add_f32_dpp v60, v60, v60 row_mirror row_mask:0xf bank_mask:0xf bound_ctrl:1
	v_pk_fma_f32 v[4:5], v[60:61], v[64:65], v[56:57] op_sel_hi:[0,1,1]
	v_pk_fma_f32 v[6:7], v[60:61], v[66:67], v[58:59] op_sel_hi:[0,1,1]
	s_waitcnt lgkmcnt(6)
	v_pk_mul_f32 v[80:81], v[4:5], v[80:81]
	v_pk_fma_f32 v[80:81], v[6:7], v[82:83], v[80:81]
	v_add_f32_e32 v80, v80, v81
	v_pk_mul_f32 v[76:77], v[76:77], v[2:3] op_sel_hi:[1,0]
	v_pk_mul_f32 v[78:79], v[78:79], v[2:3] op_sel_hi:[1,0]
	v_add_f32_dpp v80, v80, v80 quad_perm:[1,0,3,2] row_mask:0xf bank_mask:0xf bound_ctrl:1
	v_pk_fma_f32 v[76:77], v[4:5], v[68:69], v[76:77]
	v_pk_fma_f32 v[78:79], v[6:7], v[70:71], v[78:79]
	v_add_f32_dpp v80, v80, v80 quad_perm:[2,3,0,1] row_mask:0xf bank_mask:0xf bound_ctrl:1
	v_pk_mul_f32 v[52:53], v[52:53], v[4:5]
	v_pk_fma_f32 v[52:53], v[6:7], v[54:55], v[52:53]
	ds_read_b128 v[36:39], v10 offset:12800
	ds_read2st64_b32 v[0:1], v11 offset0:53 offset1:59
	ds_read_b128 v[40:43], v10 offset:13056
	ds_read_b128 v[28:31], v10 offset:12288
	ds_read_b128 v[44:47], v10 offset:13312
	ds_read_b128 v[32:35], v10 offset:12544
	v_add_f32_dpp v80, v80, v80 row_half_mirror row_mask:0xf bank_mask:0xf bound_ctrl:1
	v_add_f32_e32 v9, v52, v53
	s_nop 0
	v_add_f32_dpp v80, v80, v80 row_mirror row_mask:0xf bank_mask:0xf bound_ctrl:1
	v_pk_fma_f32 v[4:5], v[80:81], v[84:85], v[76:77] op_sel_hi:[0,1,1]
	v_pk_fma_f32 v[6:7], v[80:81], v[86:87], v[78:79] op_sel_hi:[0,1,1]
	s_waitcnt lgkmcnt(7)
	v_pk_mul_f32 v[116:117], v[4:5], v[116:117]
	v_pk_fma_f32 v[116:117], v[6:7], v[118:119], v[116:117]
	v_add_f32_e32 v116, v116, v117
	v_pk_mul_f32 v[112:113], v[112:113], v[2:3] op_sel:[0,1] op_sel_hi:[1,1]
	v_pk_mul_f32 v[114:115], v[114:115], v[2:3] op_sel:[0,1] op_sel_hi:[1,1]
	v_add_f32_dpp v116, v116, v116 quad_perm:[1,0,3,2] row_mask:0xf bank_mask:0xf bound_ctrl:1
	v_pk_fma_f32 v[112:113], v[4:5], v[104:105], v[112:113]
	v_pk_fma_f32 v[114:115], v[6:7], v[106:107], v[114:115]
	v_add_f32_dpp v116, v116, v116 quad_perm:[2,3,0,1] row_mask:0xf bank_mask:0xf bound_ctrl:1
	v_pk_mul_f32 v[72:73], v[72:73], v[4:5]
	v_pk_fma_f32 v[72:73], v[6:7], v[74:75], v[72:73]
	ds_read_b128 v[56:59], v10 offset:14336
	ds_read_b128 v[60:63], v10 offset:14592
	ds_read_b128 v[48:51], v10 offset:13824
	ds_read_b128 v[64:67], v10 offset:14848
	ds_read_b128 v[52:55], v10 offset:14080
	ds_write2st64_b32 v12, v8, v9 offset0:16 offset1:18
	v_add_f32_dpp v116, v116, v116 row_half_mirror row_mask:0xf bank_mask:0xf bound_ctrl:1
	v_add_f32_e32 v8, v72, v73
	s_nop 0
	v_add_f32_dpp v116, v116, v116 row_mirror row_mask:0xf bank_mask:0xf bound_ctrl:1
	v_pk_fma_f32 v[4:5], v[116:117], v[120:121], v[112:113] op_sel_hi:[0,1,1]
	v_pk_fma_f32 v[6:7], v[116:117], v[122:123], v[114:115] op_sel_hi:[0,1,1]
	s_waitcnt lgkmcnt(6)
	v_pk_mul_f32 v[40:41], v[4:5], v[40:41]
	v_pk_fma_f32 v[40:41], v[6:7], v[42:43], v[40:41]
	v_add_f32_e32 v40, v40, v41
	v_pk_mul_f32 v[36:37], v[36:37], v[0:1] op_sel_hi:[1,0]
	v_pk_mul_f32 v[38:39], v[38:39], v[0:1] op_sel_hi:[1,0]
	v_add_f32_dpp v40, v40, v40 quad_perm:[1,0,3,2] row_mask:0xf bank_mask:0xf bound_ctrl:1
	v_pk_fma_f32 v[36:37], v[4:5], v[28:29], v[36:37]
	v_pk_fma_f32 v[38:39], v[6:7], v[30:31], v[38:39]
	v_add_f32_dpp v40, v40, v40 quad_perm:[2,3,0,1] row_mask:0xf bank_mask:0xf bound_ctrl:1
	v_pk_mul_f32 v[108:109], v[108:109], v[4:5]
	v_pk_fma_f32 v[108:109], v[6:7], v[110:111], v[108:109]
	ds_read_b128 v[76:79], v10 offset:15872
	ds_read2st64_b32 v[2:3], v11 offset0:65 offset1:71
	ds_read_b128 v[80:83], v10 offset:16128
	ds_read_b128 v[68:71], v10 offset:15360
	ds_read_b128 v[84:87], v10 offset:16384
	ds_read_b128 v[72:75], v10 offset:15616
	v_add_f32_dpp v40, v40, v40 row_half_mirror row_mask:0xf bank_mask:0xf bound_ctrl:1
	v_add_f32_e32 v9, v108, v109
	s_nop 0
	v_add_f32_dpp v40, v40, v40 row_mirror row_mask:0xf bank_mask:0xf bound_ctrl:1
	v_pk_fma_f32 v[4:5], v[40:41], v[44:45], v[36:37] op_sel_hi:[0,1,1]
	v_pk_fma_f32 v[6:7], v[40:41], v[46:47], v[38:39] op_sel_hi:[0,1,1]
	s_waitcnt lgkmcnt(7)
	v_pk_mul_f32 v[60:61], v[4:5], v[60:61]
	v_pk_fma_f32 v[60:61], v[6:7], v[62:63], v[60:61]
	v_add_f32_e32 v60, v60, v61
	v_pk_mul_f32 v[56:57], v[56:57], v[0:1] op_sel:[0,1] op_sel_hi:[1,1]
	v_pk_mul_f32 v[58:59], v[58:59], v[0:1] op_sel:[0,1] op_sel_hi:[1,1]
	v_add_f32_dpp v60, v60, v60 quad_perm:[1,0,3,2] row_mask:0xf bank_mask:0xf bound_ctrl:1
	v_pk_fma_f32 v[56:57], v[4:5], v[48:49], v[56:57]
	v_pk_fma_f32 v[58:59], v[6:7], v[50:51], v[58:59]
	v_add_f32_dpp v60, v60, v60 quad_perm:[2,3,0,1] row_mask:0xf bank_mask:0xf bound_ctrl:1
	v_pk_mul_f32 v[32:33], v[32:33], v[4:5]
	v_pk_fma_f32 v[32:33], v[6:7], v[34:35], v[32:33]
	ds_read_b128 v[112:115], v10 offset:17408
	ds_read_b128 v[116:119], v10 offset:17664
	ds_read_b128 v[104:107], v10 offset:16896
	ds_read_b128 v[120:123], v10 offset:17920
	ds_read_b128 v[108:111], v10 offset:17152
	ds_write2st64_b32 v12, v8, v9 offset0:20 offset1:22
	v_add_f32_dpp v60, v60, v60 row_half_mirror row_mask:0xf bank_mask:0xf bound_ctrl:1
	v_add_f32_e32 v8, v32, v33
	s_nop 0
	v_add_f32_dpp v60, v60, v60 row_mirror row_mask:0xf bank_mask:0xf bound_ctrl:1
	v_pk_fma_f32 v[4:5], v[60:61], v[64:65], v[56:57] op_sel_hi:[0,1,1]
	v_pk_fma_f32 v[6:7], v[60:61], v[66:67], v[58:59] op_sel_hi:[0,1,1]
	s_waitcnt lgkmcnt(6)
	v_pk_mul_f32 v[80:81], v[4:5], v[80:81]
	v_pk_fma_f32 v[80:81], v[6:7], v[82:83], v[80:81]
	v_add_f32_e32 v80, v80, v81
	v_pk_mul_f32 v[76:77], v[76:77], v[2:3] op_sel_hi:[1,0]
	v_pk_mul_f32 v[78:79], v[78:79], v[2:3] op_sel_hi:[1,0]
	v_add_f32_dpp v80, v80, v80 quad_perm:[1,0,3,2] row_mask:0xf bank_mask:0xf bound_ctrl:1
	v_pk_fma_f32 v[76:77], v[4:5], v[68:69], v[76:77]
	v_pk_fma_f32 v[78:79], v[6:7], v[70:71], v[78:79]
	v_add_f32_dpp v80, v80, v80 quad_perm:[2,3,0,1] row_mask:0xf bank_mask:0xf bound_ctrl:1
	v_pk_mul_f32 v[52:53], v[52:53], v[4:5]
	v_pk_fma_f32 v[52:53], v[6:7], v[54:55], v[52:53]
	ds_read_b128 v[36:39], v10 offset:18944
	ds_read2st64_b32 v[0:1], v11 offset0:77 offset1:83
	ds_read_b128 v[40:43], v10 offset:19200
	ds_read_b128 v[28:31], v10 offset:18432
	ds_read_b128 v[44:47], v10 offset:19456
	ds_read_b128 v[32:35], v10 offset:18688
	v_add_f32_dpp v80, v80, v80 row_half_mirror row_mask:0xf bank_mask:0xf bound_ctrl:1
	v_add_f32_e32 v9, v52, v53
	s_nop 0
	v_add_f32_dpp v80, v80, v80 row_mirror row_mask:0xf bank_mask:0xf bound_ctrl:1
	v_pk_fma_f32 v[4:5], v[80:81], v[84:85], v[76:77] op_sel_hi:[0,1,1]
	v_pk_fma_f32 v[6:7], v[80:81], v[86:87], v[78:79] op_sel_hi:[0,1,1]
	s_waitcnt lgkmcnt(7)
	v_pk_mul_f32 v[116:117], v[4:5], v[116:117]
	v_pk_fma_f32 v[116:117], v[6:7], v[118:119], v[116:117]
	v_add_f32_e32 v116, v116, v117
	v_pk_mul_f32 v[112:113], v[112:113], v[2:3] op_sel:[0,1] op_sel_hi:[1,1]
	v_pk_mul_f32 v[114:115], v[114:115], v[2:3] op_sel:[0,1] op_sel_hi:[1,1]
	v_add_f32_dpp v116, v116, v116 quad_perm:[1,0,3,2] row_mask:0xf bank_mask:0xf bound_ctrl:1
	v_pk_fma_f32 v[112:113], v[4:5], v[104:105], v[112:113]
	v_pk_fma_f32 v[114:115], v[6:7], v[106:107], v[114:115]
	v_add_f32_dpp v116, v116, v116 quad_perm:[2,3,0,1] row_mask:0xf bank_mask:0xf bound_ctrl:1
	v_pk_mul_f32 v[72:73], v[72:73], v[4:5]
	v_pk_fma_f32 v[72:73], v[6:7], v[74:75], v[72:73]
	ds_read_b128 v[56:59], v10 offset:20480
	ds_read_b128 v[60:63], v10 offset:20736
	ds_read_b128 v[48:51], v10 offset:19968
	ds_read_b128 v[64:67], v10 offset:20992
	ds_read_b128 v[52:55], v10 offset:20224
	ds_write2st64_b32 v12, v8, v9 offset0:24 offset1:26
	v_add_f32_dpp v116, v116, v116 row_half_mirror row_mask:0xf bank_mask:0xf bound_ctrl:1
	v_add_f32_e32 v8, v72, v73
	s_nop 0
	v_add_f32_dpp v116, v116, v116 row_mirror row_mask:0xf bank_mask:0xf bound_ctrl:1
	v_pk_fma_f32 v[4:5], v[116:117], v[120:121], v[112:113] op_sel_hi:[0,1,1]
	v_pk_fma_f32 v[6:7], v[116:117], v[122:123], v[114:115] op_sel_hi:[0,1,1]
	s_waitcnt lgkmcnt(6)
	v_pk_mul_f32 v[40:41], v[4:5], v[40:41]
	v_pk_fma_f32 v[40:41], v[6:7], v[42:43], v[40:41]
	v_add_f32_e32 v40, v40, v41
	v_pk_mul_f32 v[36:37], v[36:37], v[0:1] op_sel_hi:[1,0]
	v_pk_mul_f32 v[38:39], v[38:39], v[0:1] op_sel_hi:[1,0]
	v_add_f32_dpp v40, v40, v40 quad_perm:[1,0,3,2] row_mask:0xf bank_mask:0xf bound_ctrl:1
	v_pk_fma_f32 v[36:37], v[4:5], v[28:29], v[36:37]
	v_pk_fma_f32 v[38:39], v[6:7], v[30:31], v[38:39]
	v_add_f32_dpp v40, v40, v40 quad_perm:[2,3,0,1] row_mask:0xf bank_mask:0xf bound_ctrl:1
	v_pk_mul_f32 v[108:109], v[108:109], v[4:5]
	v_pk_fma_f32 v[108:109], v[6:7], v[110:111], v[108:109]
	ds_read_b128 v[76:79], v10 offset:22016
	ds_read2st64_b32 v[2:3], v11 offset0:89 offset1:95
	ds_read_b128 v[80:83], v10 offset:22272
	ds_read_b128 v[68:71], v10 offset:21504
	ds_read_b128 v[84:87], v10 offset:22528
	ds_read_b128 v[72:75], v10 offset:21760
	v_add_f32_dpp v40, v40, v40 row_half_mirror row_mask:0xf bank_mask:0xf bound_ctrl:1
	v_add_f32_e32 v9, v108, v109
	s_nop 0
	v_add_f32_dpp v40, v40, v40 row_mirror row_mask:0xf bank_mask:0xf bound_ctrl:1
	v_pk_fma_f32 v[4:5], v[40:41], v[44:45], v[36:37] op_sel_hi:[0,1,1]
	v_pk_fma_f32 v[6:7], v[40:41], v[46:47], v[38:39] op_sel_hi:[0,1,1]
	s_waitcnt lgkmcnt(7)
	v_pk_mul_f32 v[60:61], v[4:5], v[60:61]
	v_pk_fma_f32 v[60:61], v[6:7], v[62:63], v[60:61]
	v_add_f32_e32 v60, v60, v61
	v_pk_mul_f32 v[56:57], v[56:57], v[0:1] op_sel:[0,1] op_sel_hi:[1,1]
	v_pk_mul_f32 v[58:59], v[58:59], v[0:1] op_sel:[0,1] op_sel_hi:[1,1]
	v_add_f32_dpp v60, v60, v60 quad_perm:[1,0,3,2] row_mask:0xf bank_mask:0xf bound_ctrl:1
	v_pk_fma_f32 v[56:57], v[4:5], v[48:49], v[56:57]
	v_pk_fma_f32 v[58:59], v[6:7], v[50:51], v[58:59]
	v_add_f32_dpp v60, v60, v60 quad_perm:[2,3,0,1] row_mask:0xf bank_mask:0xf bound_ctrl:1
	v_pk_mul_f32 v[32:33], v[32:33], v[4:5]
	v_pk_fma_f32 v[32:33], v[6:7], v[34:35], v[32:33]
	ds_read_b128 v[112:115], v10 offset:23552
	ds_read_b128 v[116:119], v10 offset:23808
	ds_read_b128 v[104:107], v10 offset:23040
	ds_read_b128 v[120:123], v10 offset:24064
	ds_read_b128 v[108:111], v10 offset:23296
	ds_write2st64_b32 v12, v8, v9 offset0:28 offset1:30
	v_add_f32_dpp v60, v60, v60 row_half_mirror row_mask:0xf bank_mask:0xf bound_ctrl:1
	v_add_f32_e32 v8, v32, v33
	s_nop 0
	v_add_f32_dpp v60, v60, v60 row_mirror row_mask:0xf bank_mask:0xf bound_ctrl:1
	v_pk_fma_f32 v[4:5], v[60:61], v[64:65], v[56:57] op_sel_hi:[0,1,1]
	v_pk_fma_f32 v[6:7], v[60:61], v[66:67], v[58:59] op_sel_hi:[0,1,1]
	s_waitcnt lgkmcnt(6)
	v_pk_mul_f32 v[80:81], v[4:5], v[80:81]
	v_pk_fma_f32 v[80:81], v[6:7], v[82:83], v[80:81]
	v_add_f32_e32 v80, v80, v81
	v_pk_mul_f32 v[76:77], v[76:77], v[2:3] op_sel_hi:[1,0]
	v_pk_mul_f32 v[78:79], v[78:79], v[2:3] op_sel_hi:[1,0]
	v_add_f32_dpp v80, v80, v80 quad_perm:[1,0,3,2] row_mask:0xf bank_mask:0xf bound_ctrl:1
	v_pk_fma_f32 v[76:77], v[4:5], v[68:69], v[76:77]
	v_pk_fma_f32 v[78:79], v[6:7], v[70:71], v[78:79]
	v_add_f32_dpp v80, v80, v80 quad_perm:[2,3,0,1] row_mask:0xf bank_mask:0xf bound_ctrl:1
	v_pk_mul_f32 v[52:53], v[52:53], v[4:5]
	v_pk_fma_f32 v[52:53], v[6:7], v[54:55], v[52:53]
	ds_read_b128 v[36:39], v10 offset:25088
	ds_read2st64_b32 v[0:1], v11 offset0:101 offset1:107
	ds_read_b128 v[40:43], v10 offset:25344
	ds_read_b128 v[28:31], v10 offset:24576
	ds_read_b128 v[44:47], v10 offset:25600
	ds_read_b128 v[32:35], v10 offset:24832
	v_add_f32_dpp v80, v80, v80 row_half_mirror row_mask:0xf bank_mask:0xf bound_ctrl:1
	v_add_f32_e32 v9, v52, v53
	s_nop 0
	v_add_f32_dpp v80, v80, v80 row_mirror row_mask:0xf bank_mask:0xf bound_ctrl:1
	v_pk_fma_f32 v[4:5], v[80:81], v[84:85], v[76:77] op_sel_hi:[0,1,1]
	v_pk_fma_f32 v[6:7], v[80:81], v[86:87], v[78:79] op_sel_hi:[0,1,1]
	s_waitcnt lgkmcnt(7)
	v_pk_mul_f32 v[116:117], v[4:5], v[116:117]
	v_pk_fma_f32 v[116:117], v[6:7], v[118:119], v[116:117]
	v_add_f32_e32 v116, v116, v117
	v_pk_mul_f32 v[112:113], v[112:113], v[2:3] op_sel:[0,1] op_sel_hi:[1,1]
	v_pk_mul_f32 v[114:115], v[114:115], v[2:3] op_sel:[0,1] op_sel_hi:[1,1]
	v_add_f32_dpp v116, v116, v116 quad_perm:[1,0,3,2] row_mask:0xf bank_mask:0xf bound_ctrl:1
	v_pk_fma_f32 v[112:113], v[4:5], v[104:105], v[112:113]
	v_pk_fma_f32 v[114:115], v[6:7], v[106:107], v[114:115]
	v_add_f32_dpp v116, v116, v116 quad_perm:[2,3,0,1] row_mask:0xf bank_mask:0xf bound_ctrl:1
	v_pk_mul_f32 v[72:73], v[72:73], v[4:5]
	v_pk_fma_f32 v[72:73], v[6:7], v[74:75], v[72:73]
	ds_read_b128 v[56:59], v10 offset:26624
	ds_read_b128 v[60:63], v10 offset:26880
	ds_read_b128 v[48:51], v10 offset:26112
	ds_read_b128 v[64:67], v10 offset:27136
	ds_read_b128 v[52:55], v10 offset:26368
	ds_write2st64_b32 v12, v8, v9 offset0:32 offset1:34
	v_add_f32_dpp v116, v116, v116 row_half_mirror row_mask:0xf bank_mask:0xf bound_ctrl:1
	v_add_f32_e32 v8, v72, v73
	s_nop 0
	v_add_f32_dpp v116, v116, v116 row_mirror row_mask:0xf bank_mask:0xf bound_ctrl:1
	v_pk_fma_f32 v[4:5], v[116:117], v[120:121], v[112:113] op_sel_hi:[0,1,1]
	v_pk_fma_f32 v[6:7], v[116:117], v[122:123], v[114:115] op_sel_hi:[0,1,1]
	s_waitcnt lgkmcnt(6)
	v_pk_mul_f32 v[40:41], v[4:5], v[40:41]
	v_pk_fma_f32 v[40:41], v[6:7], v[42:43], v[40:41]
	v_add_f32_e32 v40, v40, v41
	v_pk_mul_f32 v[36:37], v[36:37], v[0:1] op_sel_hi:[1,0]
	v_pk_mul_f32 v[38:39], v[38:39], v[0:1] op_sel_hi:[1,0]
	v_add_f32_dpp v40, v40, v40 quad_perm:[1,0,3,2] row_mask:0xf bank_mask:0xf bound_ctrl:1
	v_pk_fma_f32 v[36:37], v[4:5], v[28:29], v[36:37]
	v_pk_fma_f32 v[38:39], v[6:7], v[30:31], v[38:39]
	v_add_f32_dpp v40, v40, v40 quad_perm:[2,3,0,1] row_mask:0xf bank_mask:0xf bound_ctrl:1
	v_pk_mul_f32 v[108:109], v[108:109], v[4:5]
	v_pk_fma_f32 v[108:109], v[6:7], v[110:111], v[108:109]
	ds_read_b128 v[76:79], v10 offset:28160
	ds_read2st64_b32 v[2:3], v11 offset0:113 offset1:119
	ds_read_b128 v[80:83], v10 offset:28416
	ds_read_b128 v[68:71], v10 offset:27648
	ds_read_b128 v[84:87], v10 offset:28672
	ds_read_b128 v[72:75], v10 offset:27904
	v_add_f32_dpp v40, v40, v40 row_half_mirror row_mask:0xf bank_mask:0xf bound_ctrl:1
	v_add_f32_e32 v9, v108, v109
	s_nop 0
	v_add_f32_dpp v40, v40, v40 row_mirror row_mask:0xf bank_mask:0xf bound_ctrl:1
	v_pk_fma_f32 v[4:5], v[40:41], v[44:45], v[36:37] op_sel_hi:[0,1,1]
	v_pk_fma_f32 v[6:7], v[40:41], v[46:47], v[38:39] op_sel_hi:[0,1,1]
	s_waitcnt lgkmcnt(7)
	v_pk_mul_f32 v[60:61], v[4:5], v[60:61]
	v_pk_fma_f32 v[60:61], v[6:7], v[62:63], v[60:61]
	v_add_f32_e32 v60, v60, v61
	v_pk_mul_f32 v[56:57], v[56:57], v[0:1] op_sel:[0,1] op_sel_hi:[1,1]
	v_pk_mul_f32 v[58:59], v[58:59], v[0:1] op_sel:[0,1] op_sel_hi:[1,1]
	v_add_f32_dpp v60, v60, v60 quad_perm:[1,0,3,2] row_mask:0xf bank_mask:0xf bound_ctrl:1
	v_pk_fma_f32 v[56:57], v[4:5], v[48:49], v[56:57]
	v_pk_fma_f32 v[58:59], v[6:7], v[50:51], v[58:59]
	v_add_f32_dpp v60, v60, v60 quad_perm:[2,3,0,1] row_mask:0xf bank_mask:0xf bound_ctrl:1
	v_pk_mul_f32 v[32:33], v[32:33], v[4:5]
	v_pk_fma_f32 v[32:33], v[6:7], v[34:35], v[32:33]
	ds_read_b128 v[112:115], v10 offset:29696
	ds_read_b128 v[116:119], v10 offset:29952
	ds_read_b128 v[104:107], v10 offset:29184
	ds_read_b128 v[120:123], v10 offset:30208
	ds_read_b128 v[108:111], v10 offset:29440
	ds_write2st64_b32 v12, v8, v9 offset0:36 offset1:38
	v_add_f32_dpp v60, v60, v60 row_half_mirror row_mask:0xf bank_mask:0xf bound_ctrl:1
	v_add_f32_e32 v8, v32, v33
	s_nop 0
	v_add_f32_dpp v60, v60, v60 row_mirror row_mask:0xf bank_mask:0xf bound_ctrl:1
	v_pk_fma_f32 v[4:5], v[60:61], v[64:65], v[56:57] op_sel_hi:[0,1,1]
	v_pk_fma_f32 v[6:7], v[60:61], v[66:67], v[58:59] op_sel_hi:[0,1,1]
	s_waitcnt lgkmcnt(6)
	v_pk_mul_f32 v[80:81], v[4:5], v[80:81]
	v_pk_fma_f32 v[80:81], v[6:7], v[82:83], v[80:81]
	v_add_f32_e32 v80, v80, v81
	v_pk_mul_f32 v[76:77], v[76:77], v[2:3] op_sel_hi:[1,0]
	v_pk_mul_f32 v[78:79], v[78:79], v[2:3] op_sel_hi:[1,0]
	v_add_f32_dpp v80, v80, v80 quad_perm:[1,0,3,2] row_mask:0xf bank_mask:0xf bound_ctrl:1
	v_pk_fma_f32 v[76:77], v[4:5], v[68:69], v[76:77]
	v_pk_fma_f32 v[78:79], v[6:7], v[70:71], v[78:79]
	v_add_f32_dpp v80, v80, v80 quad_perm:[2,3,0,1] row_mask:0xf bank_mask:0xf bound_ctrl:1
	v_pk_mul_f32 v[52:53], v[52:53], v[4:5]
	v_pk_fma_f32 v[52:53], v[6:7], v[54:55], v[52:53]
	ds_read_b128 v[36:39], v10 offset:31232
	ds_read2st64_b32 v[0:1], v11 offset0:125 offset1:131
	ds_read_b128 v[40:43], v10 offset:31488
	ds_read_b128 v[28:31], v10 offset:30720
	ds_read_b128 v[44:47], v10 offset:31744
	ds_read_b128 v[32:35], v10 offset:30976
	v_add_f32_dpp v80, v80, v80 row_half_mirror row_mask:0xf bank_mask:0xf bound_ctrl:1
	v_add_f32_e32 v9, v52, v53
	s_nop 0
	v_add_f32_dpp v80, v80, v80 row_mirror row_mask:0xf bank_mask:0xf bound_ctrl:1
	v_pk_fma_f32 v[4:5], v[80:81], v[84:85], v[76:77] op_sel_hi:[0,1,1]
	v_pk_fma_f32 v[6:7], v[80:81], v[86:87], v[78:79] op_sel_hi:[0,1,1]
	s_waitcnt lgkmcnt(7)
	v_pk_mul_f32 v[116:117], v[4:5], v[116:117]
	v_pk_fma_f32 v[116:117], v[6:7], v[118:119], v[116:117]
	v_add_f32_e32 v116, v116, v117
	v_pk_mul_f32 v[112:113], v[112:113], v[2:3] op_sel:[0,1] op_sel_hi:[1,1]
	v_pk_mul_f32 v[114:115], v[114:115], v[2:3] op_sel:[0,1] op_sel_hi:[1,1]
	v_add_f32_dpp v116, v116, v116 quad_perm:[1,0,3,2] row_mask:0xf bank_mask:0xf bound_ctrl:1
	v_pk_fma_f32 v[112:113], v[4:5], v[104:105], v[112:113]
	v_pk_fma_f32 v[114:115], v[6:7], v[106:107], v[114:115]
	v_add_f32_dpp v116, v116, v116 quad_perm:[2,3,0,1] row_mask:0xf bank_mask:0xf bound_ctrl:1
	v_pk_mul_f32 v[72:73], v[72:73], v[4:5]
	v_pk_fma_f32 v[72:73], v[6:7], v[74:75], v[72:73]
	ds_read_b128 v[56:59], v10 offset:32768
	ds_read_b128 v[60:63], v10 offset:33024
	ds_read_b128 v[48:51], v10 offset:32256
	ds_read_b128 v[64:67], v10 offset:33280
	ds_read_b128 v[52:55], v10 offset:32512
	ds_write2st64_b32 v12, v8, v9 offset0:40 offset1:42
	v_add_f32_dpp v116, v116, v116 row_half_mirror row_mask:0xf bank_mask:0xf bound_ctrl:1
	v_add_f32_e32 v8, v72, v73
	s_nop 0
	v_add_f32_dpp v116, v116, v116 row_mirror row_mask:0xf bank_mask:0xf bound_ctrl:1
	v_pk_fma_f32 v[4:5], v[116:117], v[120:121], v[112:113] op_sel_hi:[0,1,1]
	v_pk_fma_f32 v[6:7], v[116:117], v[122:123], v[114:115] op_sel_hi:[0,1,1]
	s_waitcnt lgkmcnt(6)
	v_pk_mul_f32 v[40:41], v[4:5], v[40:41]
	v_pk_fma_f32 v[40:41], v[6:7], v[42:43], v[40:41]
	v_add_f32_e32 v40, v40, v41
	v_pk_mul_f32 v[36:37], v[36:37], v[0:1] op_sel_hi:[1,0]
	v_pk_mul_f32 v[38:39], v[38:39], v[0:1] op_sel_hi:[1,0]
	v_add_f32_dpp v40, v40, v40 quad_perm:[1,0,3,2] row_mask:0xf bank_mask:0xf bound_ctrl:1
	v_pk_fma_f32 v[36:37], v[4:5], v[28:29], v[36:37]
	v_pk_fma_f32 v[38:39], v[6:7], v[30:31], v[38:39]
	v_add_f32_dpp v40, v40, v40 quad_perm:[2,3,0,1] row_mask:0xf bank_mask:0xf bound_ctrl:1
	v_pk_mul_f32 v[108:109], v[108:109], v[4:5]
	v_pk_fma_f32 v[108:109], v[6:7], v[110:111], v[108:109]
	ds_read_b128 v[76:79], v10 offset:34304
	ds_read2st64_b32 v[2:3], v11 offset0:137 offset1:143
	ds_read_b128 v[80:83], v10 offset:34560
	ds_read_b128 v[68:71], v10 offset:33792
	ds_read_b128 v[84:87], v10 offset:34816
	ds_read_b128 v[72:75], v10 offset:34048
	v_add_f32_dpp v40, v40, v40 row_half_mirror row_mask:0xf bank_mask:0xf bound_ctrl:1
	v_add_f32_e32 v9, v108, v109
	s_nop 0
	v_add_f32_dpp v40, v40, v40 row_mirror row_mask:0xf bank_mask:0xf bound_ctrl:1
	v_pk_fma_f32 v[4:5], v[40:41], v[44:45], v[36:37] op_sel_hi:[0,1,1]
	v_pk_fma_f32 v[6:7], v[40:41], v[46:47], v[38:39] op_sel_hi:[0,1,1]
	s_waitcnt lgkmcnt(7)
	v_pk_mul_f32 v[60:61], v[4:5], v[60:61]
	v_pk_fma_f32 v[60:61], v[6:7], v[62:63], v[60:61]
	v_add_f32_e32 v60, v60, v61
	v_pk_mul_f32 v[56:57], v[56:57], v[0:1] op_sel:[0,1] op_sel_hi:[1,1]
	v_pk_mul_f32 v[58:59], v[58:59], v[0:1] op_sel:[0,1] op_sel_hi:[1,1]
	v_add_f32_dpp v60, v60, v60 quad_perm:[1,0,3,2] row_mask:0xf bank_mask:0xf bound_ctrl:1
	v_pk_fma_f32 v[56:57], v[4:5], v[48:49], v[56:57]
	v_pk_fma_f32 v[58:59], v[6:7], v[50:51], v[58:59]
	v_add_f32_dpp v60, v60, v60 quad_perm:[2,3,0,1] row_mask:0xf bank_mask:0xf bound_ctrl:1
	v_pk_mul_f32 v[32:33], v[32:33], v[4:5]
	v_pk_fma_f32 v[32:33], v[6:7], v[34:35], v[32:33]
	ds_read_b128 v[112:115], v10 offset:35840
	ds_read_b128 v[116:119], v10 offset:36096
	ds_read_b128 v[104:107], v10 offset:35328
	ds_read_b128 v[120:123], v10 offset:36352
	ds_read_b128 v[108:111], v10 offset:35584
	ds_write2st64_b32 v12, v8, v9 offset0:44 offset1:46
	v_add_f32_dpp v60, v60, v60 row_half_mirror row_mask:0xf bank_mask:0xf bound_ctrl:1
	v_add_f32_e32 v8, v32, v33
	s_nop 0
	v_add_f32_dpp v60, v60, v60 row_mirror row_mask:0xf bank_mask:0xf bound_ctrl:1
	v_pk_fma_f32 v[4:5], v[60:61], v[64:65], v[56:57] op_sel_hi:[0,1,1]
	v_pk_fma_f32 v[6:7], v[60:61], v[66:67], v[58:59] op_sel_hi:[0,1,1]
	s_waitcnt lgkmcnt(6)
	v_pk_mul_f32 v[80:81], v[4:5], v[80:81]
	v_pk_fma_f32 v[80:81], v[6:7], v[82:83], v[80:81]
	v_add_f32_e32 v80, v80, v81
	v_pk_mul_f32 v[76:77], v[76:77], v[2:3] op_sel_hi:[1,0]
	v_pk_mul_f32 v[78:79], v[78:79], v[2:3] op_sel_hi:[1,0]
	v_add_f32_dpp v80, v80, v80 quad_perm:[1,0,3,2] row_mask:0xf bank_mask:0xf bound_ctrl:1
	v_pk_fma_f32 v[76:77], v[4:5], v[68:69], v[76:77]
	v_pk_fma_f32 v[78:79], v[6:7], v[70:71], v[78:79]
	v_add_f32_dpp v80, v80, v80 quad_perm:[2,3,0,1] row_mask:0xf bank_mask:0xf bound_ctrl:1
	v_pk_mul_f32 v[52:53], v[52:53], v[4:5]
	v_pk_fma_f32 v[52:53], v[6:7], v[54:55], v[52:53]
	ds_read_b128 v[36:39], v10 offset:37376
	ds_read2st64_b32 v[0:1], v11 offset0:149 offset1:155
	ds_read_b128 v[40:43], v10 offset:37632
	ds_read_b128 v[28:31], v10 offset:36864
	ds_read_b128 v[44:47], v10 offset:37888
	ds_read_b128 v[32:35], v10 offset:37120
	v_add_f32_dpp v80, v80, v80 row_half_mirror row_mask:0xf bank_mask:0xf bound_ctrl:1
	v_add_f32_e32 v9, v52, v53
	s_nop 0
	v_add_f32_dpp v80, v80, v80 row_mirror row_mask:0xf bank_mask:0xf bound_ctrl:1
	v_pk_fma_f32 v[4:5], v[80:81], v[84:85], v[76:77] op_sel_hi:[0,1,1]
	v_pk_fma_f32 v[6:7], v[80:81], v[86:87], v[78:79] op_sel_hi:[0,1,1]
	s_waitcnt lgkmcnt(7)
	v_pk_mul_f32 v[116:117], v[4:5], v[116:117]
	v_pk_fma_f32 v[116:117], v[6:7], v[118:119], v[116:117]
	v_add_f32_e32 v116, v116, v117
	v_pk_mul_f32 v[112:113], v[112:113], v[2:3] op_sel:[0,1] op_sel_hi:[1,1]
	v_pk_mul_f32 v[114:115], v[114:115], v[2:3] op_sel:[0,1] op_sel_hi:[1,1]
	v_add_f32_dpp v116, v116, v116 quad_perm:[1,0,3,2] row_mask:0xf bank_mask:0xf bound_ctrl:1
	v_pk_fma_f32 v[112:113], v[4:5], v[104:105], v[112:113]
	v_pk_fma_f32 v[114:115], v[6:7], v[106:107], v[114:115]
	v_add_f32_dpp v116, v116, v116 quad_perm:[2,3,0,1] row_mask:0xf bank_mask:0xf bound_ctrl:1
	v_pk_mul_f32 v[72:73], v[72:73], v[4:5]
	v_pk_fma_f32 v[72:73], v[6:7], v[74:75], v[72:73]
	ds_read_b128 v[56:59], v10 offset:38912
	ds_read_b128 v[60:63], v10 offset:39168
	ds_read_b128 v[48:51], v10 offset:38400
	ds_read_b128 v[64:67], v10 offset:39424
	ds_read_b128 v[52:55], v10 offset:38656
	ds_write2st64_b32 v12, v8, v9 offset0:48 offset1:50
	v_add_f32_dpp v116, v116, v116 row_half_mirror row_mask:0xf bank_mask:0xf bound_ctrl:1
	v_add_f32_e32 v8, v72, v73
	s_nop 0
	v_add_f32_dpp v116, v116, v116 row_mirror row_mask:0xf bank_mask:0xf bound_ctrl:1
	v_pk_fma_f32 v[4:5], v[116:117], v[120:121], v[112:113] op_sel_hi:[0,1,1]
	v_pk_fma_f32 v[6:7], v[116:117], v[122:123], v[114:115] op_sel_hi:[0,1,1]
	s_waitcnt lgkmcnt(6)
	v_pk_mul_f32 v[40:41], v[4:5], v[40:41]
	v_pk_fma_f32 v[40:41], v[6:7], v[42:43], v[40:41]
	v_add_f32_e32 v40, v40, v41
	v_pk_mul_f32 v[36:37], v[36:37], v[0:1] op_sel_hi:[1,0]
	v_pk_mul_f32 v[38:39], v[38:39], v[0:1] op_sel_hi:[1,0]
	v_add_f32_dpp v40, v40, v40 quad_perm:[1,0,3,2] row_mask:0xf bank_mask:0xf bound_ctrl:1
	v_pk_fma_f32 v[36:37], v[4:5], v[28:29], v[36:37]
	v_pk_fma_f32 v[38:39], v[6:7], v[30:31], v[38:39]
	v_add_f32_dpp v40, v40, v40 quad_perm:[2,3,0,1] row_mask:0xf bank_mask:0xf bound_ctrl:1
	v_pk_mul_f32 v[108:109], v[108:109], v[4:5]
	v_pk_fma_f32 v[108:109], v[6:7], v[110:111], v[108:109]
	ds_read_b128 v[76:79], v10 offset:40448
	ds_read2st64_b32 v[2:3], v11 offset0:161 offset1:167
	ds_read_b128 v[80:83], v10 offset:40704
	ds_read_b128 v[68:71], v10 offset:39936
	ds_read_b128 v[84:87], v10 offset:40960
	ds_read_b128 v[72:75], v10 offset:40192
	v_add_f32_dpp v40, v40, v40 row_half_mirror row_mask:0xf bank_mask:0xf bound_ctrl:1
	v_add_f32_e32 v9, v108, v109
	s_nop 0
	v_add_f32_dpp v40, v40, v40 row_mirror row_mask:0xf bank_mask:0xf bound_ctrl:1
	v_pk_fma_f32 v[4:5], v[40:41], v[44:45], v[36:37] op_sel_hi:[0,1,1]
	v_pk_fma_f32 v[6:7], v[40:41], v[46:47], v[38:39] op_sel_hi:[0,1,1]
	s_waitcnt lgkmcnt(7)
	v_pk_mul_f32 v[60:61], v[4:5], v[60:61]
	v_pk_fma_f32 v[60:61], v[6:7], v[62:63], v[60:61]
	v_add_f32_e32 v60, v60, v61
	v_pk_mul_f32 v[56:57], v[56:57], v[0:1] op_sel:[0,1] op_sel_hi:[1,1]
	v_pk_mul_f32 v[58:59], v[58:59], v[0:1] op_sel:[0,1] op_sel_hi:[1,1]
	v_add_f32_dpp v60, v60, v60 quad_perm:[1,0,3,2] row_mask:0xf bank_mask:0xf bound_ctrl:1
	v_pk_fma_f32 v[56:57], v[4:5], v[48:49], v[56:57]
	v_pk_fma_f32 v[58:59], v[6:7], v[50:51], v[58:59]
	v_add_f32_dpp v60, v60, v60 quad_perm:[2,3,0,1] row_mask:0xf bank_mask:0xf bound_ctrl:1
	v_pk_mul_f32 v[32:33], v[32:33], v[4:5]
	v_pk_fma_f32 v[32:33], v[6:7], v[34:35], v[32:33]
	ds_read_b128 v[112:115], v10 offset:41984
	ds_read_b128 v[116:119], v10 offset:42240
	ds_read_b128 v[104:107], v10 offset:41472
	ds_read_b128 v[120:123], v10 offset:42496
	ds_read_b128 v[108:111], v10 offset:41728
	ds_write2st64_b32 v12, v8, v9 offset0:52 offset1:54
	v_add_f32_dpp v60, v60, v60 row_half_mirror row_mask:0xf bank_mask:0xf bound_ctrl:1
	v_add_f32_e32 v8, v32, v33
	s_nop 0
	v_add_f32_dpp v60, v60, v60 row_mirror row_mask:0xf bank_mask:0xf bound_ctrl:1
	v_pk_fma_f32 v[4:5], v[60:61], v[64:65], v[56:57] op_sel_hi:[0,1,1]
	v_pk_fma_f32 v[6:7], v[60:61], v[66:67], v[58:59] op_sel_hi:[0,1,1]
	s_waitcnt lgkmcnt(6)
	v_pk_mul_f32 v[80:81], v[4:5], v[80:81]
	v_pk_fma_f32 v[80:81], v[6:7], v[82:83], v[80:81]
	v_add_f32_e32 v80, v80, v81
	v_pk_mul_f32 v[76:77], v[76:77], v[2:3] op_sel_hi:[1,0]
	v_pk_mul_f32 v[78:79], v[78:79], v[2:3] op_sel_hi:[1,0]
	v_add_f32_dpp v80, v80, v80 quad_perm:[1,0,3,2] row_mask:0xf bank_mask:0xf bound_ctrl:1
	v_pk_fma_f32 v[76:77], v[4:5], v[68:69], v[76:77]
	v_pk_fma_f32 v[78:79], v[6:7], v[70:71], v[78:79]
	v_add_f32_dpp v80, v80, v80 quad_perm:[2,3,0,1] row_mask:0xf bank_mask:0xf bound_ctrl:1
	v_pk_mul_f32 v[52:53], v[52:53], v[4:5]
	v_pk_fma_f32 v[52:53], v[6:7], v[54:55], v[52:53]
	ds_read_b128 v[36:39], v10 offset:43520
	ds_read2st64_b32 v[0:1], v11 offset0:173 offset1:179
	ds_read_b128 v[40:43], v10 offset:43776
	ds_read_b128 v[28:31], v10 offset:43008
	ds_read_b128 v[44:47], v10 offset:44032
	ds_read_b128 v[32:35], v10 offset:43264
	v_add_f32_dpp v80, v80, v80 row_half_mirror row_mask:0xf bank_mask:0xf bound_ctrl:1
	v_add_f32_e32 v9, v52, v53
	s_nop 0
	v_add_f32_dpp v80, v80, v80 row_mirror row_mask:0xf bank_mask:0xf bound_ctrl:1
	v_pk_fma_f32 v[4:5], v[80:81], v[84:85], v[76:77] op_sel_hi:[0,1,1]
	v_pk_fma_f32 v[6:7], v[80:81], v[86:87], v[78:79] op_sel_hi:[0,1,1]
	s_waitcnt lgkmcnt(7)
	v_pk_mul_f32 v[116:117], v[4:5], v[116:117]
	v_pk_fma_f32 v[116:117], v[6:7], v[118:119], v[116:117]
	v_add_f32_e32 v116, v116, v117
	v_pk_mul_f32 v[112:113], v[112:113], v[2:3] op_sel:[0,1] op_sel_hi:[1,1]
	v_pk_mul_f32 v[114:115], v[114:115], v[2:3] op_sel:[0,1] op_sel_hi:[1,1]
	v_add_f32_dpp v116, v116, v116 quad_perm:[1,0,3,2] row_mask:0xf bank_mask:0xf bound_ctrl:1
	v_pk_fma_f32 v[112:113], v[4:5], v[104:105], v[112:113]
	v_pk_fma_f32 v[114:115], v[6:7], v[106:107], v[114:115]
	v_add_f32_dpp v116, v116, v116 quad_perm:[2,3,0,1] row_mask:0xf bank_mask:0xf bound_ctrl:1
	v_pk_mul_f32 v[72:73], v[72:73], v[4:5]
	v_pk_fma_f32 v[72:73], v[6:7], v[74:75], v[72:73]
	ds_read_b128 v[56:59], v10 offset:45056
	ds_read_b128 v[60:63], v10 offset:45312
	ds_read_b128 v[48:51], v10 offset:44544
	ds_read_b128 v[64:67], v10 offset:45568
	ds_read_b128 v[52:55], v10 offset:44800
	ds_write2st64_b32 v12, v8, v9 offset0:56 offset1:58
	v_add_f32_dpp v116, v116, v116 row_half_mirror row_mask:0xf bank_mask:0xf bound_ctrl:1
	v_add_f32_e32 v8, v72, v73
	s_nop 0
	v_add_f32_dpp v116, v116, v116 row_mirror row_mask:0xf bank_mask:0xf bound_ctrl:1
	v_pk_fma_f32 v[4:5], v[116:117], v[120:121], v[112:113] op_sel_hi:[0,1,1]
	v_pk_fma_f32 v[6:7], v[116:117], v[122:123], v[114:115] op_sel_hi:[0,1,1]
	s_waitcnt lgkmcnt(6)
	v_pk_mul_f32 v[40:41], v[4:5], v[40:41]
	v_pk_fma_f32 v[40:41], v[6:7], v[42:43], v[40:41]
	v_add_f32_e32 v40, v40, v41
	v_pk_mul_f32 v[36:37], v[36:37], v[0:1] op_sel_hi:[1,0]
	v_pk_mul_f32 v[38:39], v[38:39], v[0:1] op_sel_hi:[1,0]
	v_add_f32_dpp v40, v40, v40 quad_perm:[1,0,3,2] row_mask:0xf bank_mask:0xf bound_ctrl:1
	v_pk_fma_f32 v[36:37], v[4:5], v[28:29], v[36:37]
	v_pk_fma_f32 v[38:39], v[6:7], v[30:31], v[38:39]
	v_add_f32_dpp v40, v40, v40 quad_perm:[2,3,0,1] row_mask:0xf bank_mask:0xf bound_ctrl:1
	v_pk_mul_f32 v[108:109], v[108:109], v[4:5]
	v_pk_fma_f32 v[108:109], v[6:7], v[110:111], v[108:109]
	ds_read_b128 v[76:79], v10 offset:46592
	ds_read2st64_b32 v[2:3], v11 offset0:185 offset1:191
	ds_read_b128 v[80:83], v10 offset:46848
	ds_read_b128 v[68:71], v10 offset:46080
	ds_read_b128 v[84:87], v10 offset:47104
	ds_read_b128 v[72:75], v10 offset:46336
	v_add_f32_dpp v40, v40, v40 row_half_mirror row_mask:0xf bank_mask:0xf bound_ctrl:1
	v_add_f32_e32 v9, v108, v109
	s_nop 0
	v_add_f32_dpp v40, v40, v40 row_mirror row_mask:0xf bank_mask:0xf bound_ctrl:1
	v_pk_fma_f32 v[4:5], v[40:41], v[44:45], v[36:37] op_sel_hi:[0,1,1]
	v_pk_fma_f32 v[6:7], v[40:41], v[46:47], v[38:39] op_sel_hi:[0,1,1]
	s_waitcnt lgkmcnt(7)
	v_pk_mul_f32 v[60:61], v[4:5], v[60:61]
	v_pk_fma_f32 v[60:61], v[6:7], v[62:63], v[60:61]
	v_add_f32_e32 v60, v60, v61
	v_pk_mul_f32 v[56:57], v[56:57], v[0:1] op_sel:[0,1] op_sel_hi:[1,1]
	v_pk_mul_f32 v[58:59], v[58:59], v[0:1] op_sel:[0,1] op_sel_hi:[1,1]
	v_add_f32_dpp v60, v60, v60 quad_perm:[1,0,3,2] row_mask:0xf bank_mask:0xf bound_ctrl:1
	v_pk_fma_f32 v[56:57], v[4:5], v[48:49], v[56:57]
	v_pk_fma_f32 v[58:59], v[6:7], v[50:51], v[58:59]
	v_add_f32_dpp v60, v60, v60 quad_perm:[2,3,0,1] row_mask:0xf bank_mask:0xf bound_ctrl:1
	v_pk_mul_f32 v[32:33], v[32:33], v[4:5]
	v_pk_fma_f32 v[32:33], v[6:7], v[34:35], v[32:33]
	ds_read_b128 v[112:115], v10 offset:48128
	ds_read_b128 v[116:119], v10 offset:48384
	ds_read_b128 v[104:107], v10 offset:47616
	ds_read_b128 v[120:123], v10 offset:48640
	ds_read_b128 v[108:111], v10 offset:47872
	ds_write2st64_b32 v12, v8, v9 offset0:60 offset1:62
	v_add_f32_dpp v60, v60, v60 row_half_mirror row_mask:0xf bank_mask:0xf bound_ctrl:1
	v_add_f32_e32 v8, v32, v33
	s_nop 0
	v_add_f32_dpp v60, v60, v60 row_mirror row_mask:0xf bank_mask:0xf bound_ctrl:1

.LBB0_826:
	s_and_saveexec_b64 s[8:9], s[26:27]
	s_cbranch_execz .Lscan_epi_done
	v_mov_b32_e32 v12, v102
	v_pk_fma_f32 v[4:5], v[60:61], v[64:65], v[56:57] op_sel_hi:[0,1,1]
	v_pk_fma_f32 v[6:7], v[60:61], v[66:67], v[58:59] op_sel_hi:[0,1,1]
	v_pk_mul_f32 v[80:81], v[4:5], v[80:81]
	v_pk_fma_f32 v[80:81], v[6:7], v[82:83], v[80:81]
	v_add_f32_e32 v80, v80, v81
	v_pk_mul_f32 v[76:77], v[76:77], v[2:3] op_sel_hi:[1,0]
	v_pk_mul_f32 v[78:79], v[78:79], v[2:3] op_sel_hi:[1,0]
	v_add_f32_dpp v80, v80, v80 quad_perm:[1,0,3,2] row_mask:0xf bank_mask:0xf bound_ctrl:1
	v_pk_fma_f32 v[76:77], v[4:5], v[68:69], v[76:77]
	v_pk_fma_f32 v[78:79], v[6:7], v[70:71], v[78:79]
	v_add_f32_dpp v80, v80, v80 quad_perm:[2,3,0,1] row_mask:0xf bank_mask:0xf bound_ctrl:1
	v_pk_mul_f32 v[52:53], v[52:53], v[4:5]
	v_pk_fma_f32 v[52:53], v[6:7], v[54:55], v[52:53]
	v_add_f32_dpp v80, v80, v80 row_half_mirror row_mask:0xf bank_mask:0xf bound_ctrl:1
	v_add_f32_e32 v9, v52, v53
	s_nop 0
	v_add_f32_dpp v80, v80, v80 row_mirror row_mask:0xf bank_mask:0xf bound_ctrl:1
	v_pk_fma_f32 v[4:5], v[80:81], v[84:85], v[76:77] op_sel_hi:[0,1,1]
	v_pk_fma_f32 v[6:7], v[80:81], v[86:87], v[78:79] op_sel_hi:[0,1,1]
	v_pk_mul_f32 v[116:117], v[4:5], v[116:117]
	v_pk_fma_f32 v[116:117], v[6:7], v[118:119], v[116:117]
	v_add_f32_e32 v116, v116, v117
	v_pk_mul_f32 v[112:113], v[112:113], v[2:3] op_sel:[0,1] op_sel_hi:[1,1]
	v_pk_mul_f32 v[114:115], v[114:115], v[2:3] op_sel:[0,1] op_sel_hi:[1,1]
	v_add_f32_dpp v116, v116, v116 quad_perm:[1,0,3,2] row_mask:0xf bank_mask:0xf bound_ctrl:1
	v_pk_fma_f32 v[112:113], v[4:5], v[104:105], v[112:113]
	v_pk_fma_f32 v[114:115], v[6:7], v[106:107], v[114:115]
	v_add_f32_dpp v116, v116, v116 quad_perm:[2,3,0,1] row_mask:0xf bank_mask:0xf bound_ctrl:1
	v_pk_mul_f32 v[72:73], v[72:73], v[4:5]
	v_pk_fma_f32 v[72:73], v[6:7], v[74:75], v[72:73]
	ds_write2st64_b32 v12, v8, v9 offset0:0 offset1:2
	v_add_f32_dpp v116, v116, v116 row_half_mirror row_mask:0xf bank_mask:0xf bound_ctrl:1
	v_add_f32_e32 v8, v72, v73
	s_nop 0
	v_add_f32_dpp v116, v116, v116 row_mirror row_mask:0xf bank_mask:0xf bound_ctrl:1
	v_pk_fma_f32 v[4:5], v[116:117], v[120:121], v[112:113] op_sel_hi:[0,1,1]
	v_pk_fma_f32 v[6:7], v[116:117], v[122:123], v[114:115] op_sel_hi:[0,1,1]
	v_pk_mul_f32 v[108:109], v[108:109], v[4:5]
	v_pk_fma_f32 v[108:109], v[6:7], v[110:111], v[108:109]
	v_add_f32_e32 v9, v108, v109
	s_nop 0
	s_nop 1
	ds_write2st64_b32 v12, v8, v9 offset0:4 offset1:6
	s_nop 0
	s_nop 0
